# v68 + non-temporal hint on mixer-A's streaming LOADS only (stores stay cached for P3a)
# speedup vs baseline: 1.0045x; 1.0045x over previous
.LBB0_650:
	v_lshl_add_u64 v[44:45], v[66:67], 0, s[20:21]
	v_add_co_u32_e32 v36, vcc, s39, v44
	s_waitcnt vmcnt(3)
	v_pk_mul_f32 v[42:43], v[6:7], v[42:43]
	v_addc_co_u32_e32 v37, vcc, -1, v45, vcc
	v_add_co_u32_e32 v108, vcc, s40, v66
	global_load_dwordx4 v[76:79], v[36:37], off offset:-2048 nt
	s_nop 0
	v_addc_co_u32_e32 v109, vcc, -1, v67, vcc
	v_add_co_u32_e32 v46, vcc, s41, v44
	global_load_dwordx4 v[80:83], v[108:109], off offset:-2048 nt
	s_nop 0
	v_addc_co_u32_e32 v47, vcc, -1, v45, vcc
	v_add_co_u32_e32 v72, vcc, s42, v66
	global_load_dwordx4 v[84:87], v[46:47], off offset:-4096 nt
	s_nop 0
	v_addc_co_u32_e32 v73, vcc, -1, v67, vcc
	global_load_dwordx4 v[88:91], v[72:73], off offset:-4096 nt
	global_load_dwordx4 v[48:51], v[66:67], off offset:-2048 nt
	global_load_dwordx4 v[36:39], v[66:67], off nt
	global_load_dwordx4 v[92:95], v[72:73], off offset:-2048 nt
	global_load_dwordx4 v[96:99], v[72:73], off nt
	global_load_dwordx4 v[100:103], v[46:47], off offset:-2048 nt
	v_add_co_u32_e32 v70, vcc, s44, v66
	v_pk_mul_f32 v[40:41], v[4:5], v[40:41]
	s_nop 0
	v_addc_co_u32_e32 v71, vcc, -1, v67, vcc
	v_add_co_u32_e32 v52, vcc, s43, v44
	s_waitcnt vmcnt(11)
	v_pk_mul_f32 v[34:35], v[2:3], v[34:35]
	v_addc_co_u32_e32 v53, vcc, -1, v45, vcc
	v_add_co_u32_e32 v44, vcc, s45, v44
	v_pk_mul_f32 v[32:33], v[0:1], v[32:33]
	s_nop 0
	v_addc_co_u32_e32 v45, vcc, -1, v45, vcc
	s_waitcnt vmcnt(10)
	v_pk_fma_f32 v[110:111], v[14:15], v[30:31], v[42:43]
	v_pk_fma_f32 v[112:113], v[12:13], v[28:29], v[40:41]
	s_waitcnt vmcnt(9)
	v_pk_fma_f32 v[114:115], v[10:11], v[26:27], v[34:35]
	v_pk_fma_f32 v[116:117], v[8:9], v[24:25], v[32:33]
	global_load_dwordx4 v[104:107], v[46:47], off nt
	global_load_dwordx4 v[60:63], v[52:53], off offset:-2048 nt
	global_load_dwordx4 v[56:59], v[70:71], off offset:-2048 nt
	s_nop 0
	global_load_dwordx4 v[52:55], v[44:45], off offset:-4096 nt
	global_load_dwordx4 v[32:35], v[44:45], off offset:-2048 nt
	global_load_dwordx4 v[40:43], v[66:67], off offset:-4096 nt
	s_nop 0
	global_load_dwordx4 v[44:47], v[44:45], off nt
	s_add_i32 s24, s14, 14
	s_cmp_gt_u32 s24, 61
	s_cselect_b64 s[24:25], -1, 0
	s_and_b64 s[24:25], s[22:23], s[24:25]
	s_andn2_b64 vcc, exec, s[24:25]
	s_waitcnt vmcnt(15)
	v_lshlrev_b32_e32 v118, 16, v76
	v_and_b32_e32 v119, 0xffff0000, v76
	v_lshlrev_b32_e32 v120, 16, v77
	v_and_b32_e32 v121, 0xffff0000, v77
	v_lshlrev_b32_e32 v122, 16, v78
	v_and_b32_e32 v123, 0xffff0000, v78
	v_lshlrev_b32_e32 v124, 16, v79
	v_and_b32_e32 v125, 0xffff0000, v79
	s_waitcnt vmcnt(14)
	v_lshlrev_b32_e32 v76, 16, v80
	v_and_b32_e32 v77, 0xffff0000, v80
	v_lshlrev_b32_e32 v78, 16, v81
	v_and_b32_e32 v79, 0xffff0000, v81
	v_pk_fma_f32 v[112:113], v[20:21], v[118:119], v[112:113]
	v_pk_fma_f32 v[110:111], v[22:23], v[120:121], v[110:111]
	v_lshlrev_b32_e32 v80, 16, v82
	v_and_b32_e32 v81, 0xffff0000, v82
	v_lshlrev_b32_e32 v82, 16, v83
	v_and_b32_e32 v83, 0xffff0000, v83
	v_pk_fma_f32 v[116:117], v[16:17], v[122:123], v[116:117]
	v_pk_fma_f32 v[114:115], v[18:19], v[124:125], v[114:115]
	v_pk_mul_f32 v[78:79], v[110:111], v[78:79]
	v_pk_mul_f32 v[76:77], v[112:113], v[76:77]
	v_pk_mul_f32 v[82:83], v[114:115], v[82:83]
	v_pk_mul_f32 v[80:81], v[116:117], v[80:81]
	v_cvt_pk_bf16_f32 v76, v76, v77
	v_cvt_pk_bf16_f32 v77, v78, v79
	s_waitcnt vmcnt(13)
	v_lshlrev_b32_e32 v128, 16, v86
	v_cvt_pk_bf16_f32 v78, v80, v81
	v_cvt_pk_bf16_f32 v79, v82, v83
	global_store_dwordx4 v[108:109], v[76:79], off offset:-2048
	v_and_b32_e32 v129, 0xffff0000, v86
	s_waitcnt vmcnt(13)
	v_lshlrev_b32_e32 v80, 16, v89
	v_lshlrev_b32_e32 v76, 16, v87
	v_and_b32_e32 v77, 0xffff0000, v87
	v_lshlrev_b32_e32 v78, 16, v88
	v_and_b32_e32 v79, 0xffff0000, v88
	v_and_b32_e32 v81, 0xffff0000, v89
	v_lshlrev_b32_e32 v82, 16, v90
	v_and_b32_e32 v83, 0xffff0000, v90
	v_lshlrev_b32_e32 v86, 16, v91
	v_and_b32_e32 v87, 0xffff0000, v91
	v_pk_mul_f32 v[88:89], v[12:13], v[118:119]
	v_pk_mul_f32 v[90:91], v[14:15], v[120:121]
	v_lshlrev_b32_e32 v126, 16, v84
	v_and_b32_e32 v127, 0xffff0000, v84
	v_lshlrev_b32_e32 v84, 16, v85
	v_and_b32_e32 v85, 0xffff0000, v85
	v_pk_fma_f32 v[30:31], v[6:7], v[30:31], v[90:91]
	v_pk_fma_f32 v[28:29], v[4:5], v[28:29], v[88:89]
	v_pk_fma_f32 v[30:31], v[22:23], v[84:85], v[30:31]
	v_pk_fma_f32 v[28:29], v[20:21], v[126:127], v[28:29]
	v_pk_mul_f32 v[30:31], v[30:31], v[80:81]
	v_pk_mul_f32 v[28:29], v[28:29], v[78:79]
	v_pk_mul_f32 v[78:79], v[8:9], v[122:123]
	v_pk_mul_f32 v[80:81], v[10:11], v[124:125]
	v_pk_fma_f32 v[24:25], v[0:1], v[24:25], v[78:79]
	v_pk_fma_f32 v[26:27], v[2:3], v[26:27], v[80:81]
	v_pk_fma_f32 v[24:25], v[16:17], v[128:129], v[24:25]
	v_pk_fma_f32 v[26:27], v[18:19], v[76:77], v[26:27]
	v_pk_mul_f32 v[90:91], v[14:15], v[84:85]
	v_pk_mul_f32 v[78:79], v[26:27], v[86:87]
	v_pk_mul_f32 v[26:27], v[24:25], v[82:83]
	v_cvt_pk_bf16_f32 v24, v28, v29
	v_cvt_pk_bf16_f32 v25, v30, v31
	s_waitcnt vmcnt(8)
	v_lshlrev_b32_e32 v30, 16, v101
	v_cvt_pk_bf16_f32 v26, v26, v27
	v_cvt_pk_bf16_f32 v27, v78, v79
	v_and_b32_e32 v31, 0xffff0000, v101
	v_pk_mul_f32 v[88:89], v[12:13], v[126:127]
	v_pk_fma_f32 v[90:91], v[6:7], v[120:121], v[90:91]
	global_store_dwordx4 v[72:73], v[24:27], off offset:-4096
	v_lshlrev_b32_e32 v28, 16, v100
	v_and_b32_e32 v29, 0xffff0000, v100
	v_lshlrev_b32_e32 v26, 16, v93
	v_and_b32_e32 v27, 0xffff0000, v93
	v_pk_fma_f32 v[88:89], v[4:5], v[118:119], v[88:89]
	v_pk_fma_f32 v[90:91], v[22:23], v[30:31], v[90:91]
	v_lshlrev_b32_e32 v24, 16, v92
	v_and_b32_e32 v25, 0xffff0000, v92
	v_pk_fma_f32 v[88:89], v[20:21], v[28:29], v[88:89]
	v_pk_mul_f32 v[26:27], v[90:91], v[26:27]
	v_pk_mul_f32 v[90:91], v[10:11], v[76:77]
	v_lshlrev_b32_e32 v80, 16, v103
	v_and_b32_e32 v81, 0xffff0000, v103
	v_pk_mul_f32 v[24:25], v[88:89], v[24:25]
	v_pk_mul_f32 v[88:89], v[8:9], v[128:129]
	v_pk_fma_f32 v[90:91], v[2:3], v[124:125], v[90:91]
	v_lshlrev_b32_e32 v78, 16, v102
	v_and_b32_e32 v79, 0xffff0000, v102
	v_lshlrev_b32_e32 v86, 16, v95
	v_and_b32_e32 v87, 0xffff0000, v95
	v_pk_fma_f32 v[88:89], v[0:1], v[122:123], v[88:89]
	v_pk_fma_f32 v[90:91], v[18:19], v[80:81], v[90:91]
	v_lshlrev_b32_e32 v82, 16, v94
	v_and_b32_e32 v83, 0xffff0000, v94
	v_pk_fma_f32 v[88:89], v[16:17], v[78:79], v[88:89]
	v_pk_mul_f32 v[86:87], v[90:91], v[86:87]
	v_lshlrev_b32_e32 v92, 16, v98
	v_and_b32_e32 v93, 0xffff0000, v98
	v_lshlrev_b32_e32 v94, 16, v99
	v_and_b32_e32 v95, 0xffff0000, v99
	v_pk_mul_f32 v[98:99], v[14:15], v[30:31]
	v_pk_mul_f32 v[82:83], v[88:89], v[82:83]
	v_cvt_pk_bf16_f32 v24, v24, v25
	v_cvt_pk_bf16_f32 v25, v26, v27
	v_pk_fma_f32 v[84:85], v[6:7], v[84:85], v[98:99]
	v_cvt_pk_bf16_f32 v26, v82, v83
	v_cvt_pk_bf16_f32 v27, v86, v87
	s_waitcnt vmcnt(8)
	v_lshlrev_b32_e32 v86, 16, v105
	v_and_b32_e32 v87, 0xffff0000, v105
	global_store_dwordx4 v[72:73], v[24:27], off offset:-2048
	v_pk_fma_f32 v[84:85], v[22:23], v[86:87], v[84:85]
	v_lshlrev_b32_e32 v82, 16, v104
	v_lshlrev_b32_e32 v24, 16, v96
	v_and_b32_e32 v25, 0xffff0000, v96
	v_lshlrev_b32_e32 v26, 16, v97
	v_and_b32_e32 v27, 0xffff0000, v97
	v_pk_mul_f32 v[96:97], v[12:13], v[28:29]
	v_and_b32_e32 v83, 0xffff0000, v104
	v_pk_fma_f32 v[96:97], v[4:5], v[126:127], v[96:97]
	v_pk_mul_f32 v[26:27], v[84:85], v[26:27]
	v_pk_mul_f32 v[84:85], v[8:9], v[78:79]
	v_lshlrev_b32_e32 v88, 16, v106
	v_and_b32_e32 v89, 0xffff0000, v106
	v_pk_fma_f32 v[96:97], v[20:21], v[82:83], v[96:97]
	v_pk_fma_f32 v[84:85], v[0:1], v[128:129], v[84:85]
	v_pk_mul_f32 v[24:25], v[96:97], v[24:25]
	v_pk_mul_f32 v[96:97], v[10:11], v[80:81]
	v_pk_fma_f32 v[84:85], v[16:17], v[88:89], v[84:85]
	v_lshlrev_b32_e32 v90, 16, v107
	v_and_b32_e32 v91, 0xffff0000, v107
	v_pk_fma_f32 v[76:77], v[2:3], v[76:77], v[96:97]
	v_pk_mul_f32 v[84:85], v[84:85], v[92:93]
	v_pk_fma_f32 v[76:77], v[18:19], v[90:91], v[76:77]
	v_cvt_pk_bf16_f32 v24, v24, v25
	v_cvt_pk_bf16_f32 v25, v26, v27
	v_cvt_pk_bf16_f32 v26, v84, v85
	v_pk_mul_f32 v[84:85], v[12:13], v[82:83]
	v_pk_mul_f32 v[92:93], v[14:15], v[86:87]
	v_pk_mul_f32 v[76:77], v[76:77], v[94:95]
	v_pk_fma_f32 v[30:31], v[6:7], v[30:31], v[92:93]
	v_cvt_pk_bf16_f32 v27, v76, v77
	global_store_dwordx4 v[72:73], v[24:27], off
	s_waitcnt vmcnt(9)
	v_lshlrev_b32_e32 v72, 16, v60
	v_and_b32_e32 v73, 0xffff0000, v60
	v_lshlrev_b32_e32 v60, 16, v61
	v_and_b32_e32 v61, 0xffff0000, v61
	v_pk_fma_f32 v[28:29], v[4:5], v[28:29], v[84:85]
	s_waitcnt vmcnt(8)
	v_lshlrev_b32_e32 v24, 16, v56
	v_and_b32_e32 v25, 0xffff0000, v56
	v_lshlrev_b32_e32 v26, 16, v57
	v_and_b32_e32 v27, 0xffff0000, v57
	v_pk_fma_f32 v[28:29], v[20:21], v[72:73], v[28:29]
	v_pk_fma_f32 v[30:31], v[22:23], v[60:61], v[30:31]
	v_pk_mul_f32 v[24:25], v[28:29], v[24:25]
	v_pk_mul_f32 v[26:27], v[30:31], v[26:27]
	v_pk_mul_f32 v[28:29], v[8:9], v[88:89]
	v_pk_mul_f32 v[30:31], v[10:11], v[90:91]
	v_lshlrev_b32_e32 v76, 16, v62
	v_and_b32_e32 v77, 0xffff0000, v62
	v_lshlrev_b32_e32 v62, 16, v63
	v_and_b32_e32 v63, 0xffff0000, v63
	v_pk_fma_f32 v[30:31], v[2:3], v[80:81], v[30:31]
	v_pk_fma_f32 v[28:29], v[0:1], v[78:79], v[28:29]
	v_lshlrev_b32_e32 v56, 16, v58
	v_and_b32_e32 v57, 0xffff0000, v58
	v_lshlrev_b32_e32 v58, 16, v59
	v_and_b32_e32 v59, 0xffff0000, v59
	v_pk_fma_f32 v[28:29], v[16:17], v[76:77], v[28:29]
	v_pk_fma_f32 v[30:31], v[18:19], v[62:63], v[30:31]
	v_pk_mul_f32 v[28:29], v[28:29], v[56:57]
	v_pk_mul_f32 v[30:31], v[30:31], v[58:59]
	v_cvt_pk_bf16_f32 v24, v24, v25
	v_cvt_pk_bf16_f32 v25, v26, v27
	v_cvt_pk_bf16_f32 v26, v28, v29
	s_waitcnt vmcnt(5)
	v_lshlrev_b32_e32 v28, 16, v42
	v_cvt_pk_bf16_f32 v27, v30, v31
	global_store_dwordx4 v[70:71], v[24:27], off offset:-2048
	v_and_b32_e32 v29, 0xffff0000, v42
	v_lshlrev_b32_e32 v30, 16, v43
	v_lshlrev_b32_e32 v24, 16, v40
	v_and_b32_e32 v25, 0xffff0000, v40
	v_lshlrev_b32_e32 v26, 16, v41
	v_and_b32_e32 v27, 0xffff0000, v41
	v_and_b32_e32 v31, 0xffff0000, v43
	v_pk_mul_f32 v[40:41], v[12:13], v[72:73]
	v_pk_mul_f32 v[42:43], v[14:15], v[60:61]
	v_lshlrev_b32_e32 v56, 16, v52
	v_and_b32_e32 v57, 0xffff0000, v52
	v_lshlrev_b32_e32 v58, 16, v53
	v_and_b32_e32 v59, 0xffff0000, v53
	v_pk_fma_f32 v[42:43], v[6:7], v[86:87], v[42:43]
	v_pk_fma_f32 v[40:41], v[4:5], v[82:83], v[40:41]
	v_pk_fma_f32 v[42:43], v[22:23], v[58:59], v[42:43]
	v_pk_fma_f32 v[40:41], v[20:21], v[56:57], v[40:41]
	v_pk_mul_f32 v[26:27], v[42:43], v[26:27]
	v_pk_mul_f32 v[24:25], v[40:41], v[24:25]
	v_pk_mul_f32 v[40:41], v[8:9], v[76:77]
	v_pk_mul_f32 v[42:43], v[10:11], v[62:63]
	v_lshlrev_b32_e32 v52, 16, v54
	v_and_b32_e32 v53, 0xffff0000, v54
	v_lshlrev_b32_e32 v54, 16, v55
	v_and_b32_e32 v55, 0xffff0000, v55
	v_pk_fma_f32 v[42:43], v[2:3], v[90:91], v[42:43]
	v_pk_fma_f32 v[40:41], v[0:1], v[88:89], v[40:41]
	v_pk_fma_f32 v[42:43], v[18:19], v[54:55], v[42:43]
	v_pk_fma_f32 v[40:41], v[16:17], v[52:53], v[40:41]
	v_pk_mul_f32 v[30:31], v[42:43], v[30:31]
	v_pk_mul_f32 v[28:29], v[40:41], v[28:29]
	v_cvt_pk_bf16_f32 v24, v24, v25
	v_cvt_pk_bf16_f32 v25, v26, v27
	v_lshlrev_b32_e32 v40, 16, v32
	v_cvt_pk_bf16_f32 v26, v28, v29
	v_cvt_pk_bf16_f32 v27, v30, v31
	global_store_dwordx4 v[66:67], v[24:27], off offset:-4096
	v_lshlrev_b32_e32 v28, 16, v50
	v_and_b32_e32 v29, 0xffff0000, v50
	v_lshlrev_b32_e32 v24, 16, v48
	v_and_b32_e32 v25, 0xffff0000, v48
	v_lshlrev_b32_e32 v26, 16, v49
	v_and_b32_e32 v27, 0xffff0000, v49
	v_lshlrev_b32_e32 v30, 16, v51
	v_and_b32_e32 v31, 0xffff0000, v51
	v_pk_mul_f32 v[48:49], v[12:13], v[56:57]
	v_pk_mul_f32 v[50:51], v[14:15], v[58:59]
	v_and_b32_e32 v41, 0xffff0000, v32
	v_lshlrev_b32_e32 v42, 16, v33
	v_and_b32_e32 v43, 0xffff0000, v33
	v_pk_fma_f32 v[50:51], v[6:7], v[60:61], v[50:51]
	v_pk_fma_f32 v[48:49], v[4:5], v[72:73], v[48:49]
	v_pk_fma_f32 v[50:51], v[22:23], v[42:43], v[50:51]
	v_pk_fma_f32 v[48:49], v[20:21], v[40:41], v[48:49]
	v_pk_mul_f32 v[26:27], v[50:51], v[26:27]
	v_pk_mul_f32 v[24:25], v[48:49], v[24:25]
	v_pk_mul_f32 v[48:49], v[8:9], v[52:53]
	v_pk_mul_f32 v[50:51], v[10:11], v[54:55]
	v_lshlrev_b32_e32 v32, 16, v34
	v_and_b32_e32 v33, 0xffff0000, v34
	v_lshlrev_b32_e32 v34, 16, v35
	v_and_b32_e32 v35, 0xffff0000, v35
	v_pk_fma_f32 v[50:51], v[2:3], v[62:63], v[50:51]
	v_pk_fma_f32 v[48:49], v[0:1], v[76:77], v[48:49]
	v_pk_fma_f32 v[50:51], v[18:19], v[34:35], v[50:51]
	v_pk_fma_f32 v[48:49], v[16:17], v[32:33], v[48:49]
	v_pk_mul_f32 v[30:31], v[50:51], v[30:31]
	v_pk_mul_f32 v[28:29], v[48:49], v[28:29]
	v_cvt_pk_bf16_f32 v24, v24, v25
	v_cvt_pk_bf16_f32 v25, v26, v27
	s_nop 0
	v_cvt_pk_bf16_f32 v26, v28, v29
	v_cvt_pk_bf16_f32 v27, v30, v31
	global_store_dwordx4 v[66:67], v[24:27], off offset:-2048
	s_cbranch_vccnz .LBB0_652
	global_store_dwordx4 v[68:69], v[40:43], off
	global_store_dwordx4 v[68:69], v[32:35], off offset:16
